# grid barrier follower path: L1 invalidate of the acquire issued before the wait on the XCD generation word (overlaps the wait); on top of the attention unit re-indexing
# speedup vs baseline: 1.0097x; 1.0061x over previous
; __device__ __forceinline__ unsigned xb_ld(unsigned* p)              { return __hip_atomic_load(p, __ATOMIC_RELAXED, __HIP_MEMORY_SCOPE_AGENT); }
; __device__ __forceinline__ unsigned xb_add(unsigned* p, unsigned v) { return __hip_atomic_fetch_add(p, v, __ATOMIC_RELAXED, __HIP_MEMORY_SCOPE_AGENT); }
; #define XB_SPIN(cond, bar) do { unsigned _sp = 0; while (cond) { __builtin_amdgcn_s_sleep(1); \
;     if ((++_sp & 255u) == 0u) { if (xb_ld(&(bar)[XB_TMO])) break; if (_sp > XB_SPIN_CAP) { atomicAdd(&(bar)[XB_TMO], 1u); break; } } } } while (0)
; __device__ __forceinline__ void grid_barrier(unsigned* bar, unsigned x, volatile LAS unsigned* st, unsigned G, int wv) {
;     ...
;         const unsigned old = xb_add(&bar[XB_XSUB(x)], 1u);
;         const unsigned gen = old / nloc;
;         if (old + 1u == (gen + 1u) * nloc) {
;             __builtin_amdgcn_fence(__ATOMIC_RELEASE, "agent");
;             asm volatile("s_waitcnt vmcnt(0)" ::: "memory");
;             const unsigned og = xb_add(&bar[XB_TOP], 1u);
;             const unsigned tg = og / nx;
;             if (og + 1u == (tg + 1u) * nx) xb_add(&bar[XB_TOPGEN], 1u);
;             else XB_SPIN(xb_ld(&bar[XB_TOPGEN]) == tg, bar);
;             __builtin_amdgcn_fence(__ATOMIC_ACQUIRE, "agent");
;             xb_add(&bar[XB_XGEN(x)], 1u);
;             asm volatile("s_waitcnt vmcnt(0)" ::: "memory");
;         } else {
;             XB_SPIN(xb_ld(&bar[XB_XGEN(x)]) == gen, bar);
;             __builtin_amdgcn_fence(__ATOMIC_ACQUIRE, "agent");
.LBB0_144:
	s_or_b64 exec, exec, s[10:11]
	v_cvt_f32_u32_e32 v4, v2
	s_waitcnt vmcnt(0)
	v_readfirstlane_b32 s8, v3
	v_sub_u32_e32 v3, 0, v2
	v_rcp_iflag_f32_e32 v4, v4
	v_add_u32_e32 v5, s8, v1
	v_mul_f32_e32 v4, 0x4f7ffffe, v4
	v_cvt_u32_f32_e32 v4, v4
	v_mul_lo_u32 v1, v3, v4
	v_mul_hi_u32 v1, v4, v1
	v_add_u32_e32 v1, v4, v1
	v_mul_hi_u32 v1, v5, v1
	v_mul_lo_u32 v3, v1, v2
	v_sub_u32_e32 v3, v5, v3
	v_add_u32_e32 v4, 1, v1
	v_cmp_ge_u32_e32 vcc, v3, v2
	s_nop 1
	v_cndmask_b32_e32 v1, v1, v4, vcc
	v_sub_u32_e32 v4, v3, v2
	v_cndmask_b32_e32 v3, v3, v4, vcc
	v_add_u32_e32 v4, 1, v1
	v_cmp_ge_u32_e32 vcc, v3, v2
	v_add_u32_e32 v3, 1, v5
	s_nop 0
	v_cndmask_b32_e32 v1, v1, v4, vcc
	v_mul_lo_u32 v4, v2, v1
	v_add_u32_e32 v2, v4, v2
	v_cmp_ne_u32_e32 vcc, v3, v2
	s_and_saveexec_b64 s[8:9], vcc
	s_xor_b64 s[8:9], exec, s[8:9]
	s_cbranch_execz .LBB0_158
	s_waitcnt lgkmcnt(0)
	buffer_inv sc1
	v_mov_b32_e32 v0, 0x2000
	global_load_dword v0, v0, s[6:7] offset:1024 sc1
	s_add_u32 s12, s6, 0x2400
	s_addc_u32 s13, s7, 0
	s_waitcnt vmcnt(0)
	v_cmp_eq_u32_e32 vcc, v0, v1
	s_and_saveexec_b64 s[10:11], vcc
	s_cbranch_execz .LBB0_157
	s_mov_b32 s24, 1
	s_mov_b64 s[14:15], 0
	v_mov_b32_e32 v0, 0
	s_branch .LBB0_148

; __device__ __forceinline__ unsigned xb_ld(unsigned* p)              { return __hip_atomic_load(p, __ATOMIC_RELAXED, __HIP_MEMORY_SCOPE_AGENT); }
; #define XB_SPIN(cond, bar) do { unsigned _sp = 0; while (cond) { __builtin_amdgcn_s_sleep(1); \
;     if ((++_sp & 255u) == 0u) { if (xb_ld(&(bar)[XB_TMO])) break; if (_sp > XB_SPIN_CAP) { atomicAdd(&(bar)[XB_TMO], 1u); break; } } } } while (0)
; __device__ __forceinline__ void grid_barrier(unsigned* bar, unsigned x, volatile LAS unsigned* st, unsigned G, int wv) {
;     ...
;             XB_SPIN(xb_ld(&bar[XB_XGEN(x)]) == gen, bar);
;             __builtin_amdgcn_fence(__ATOMIC_ACQUIRE, "agent");
;             asm volatile("s_waitcnt vmcnt(0)" ::: "memory");
.LBB0_157:
	s_or_b64 exec, exec, s[10:11]
	s_waitcnt vmcnt(0)
	s_waitcnt vmcnt(0)

; __device__ __forceinline__ unsigned xb_ld(unsigned* p)              { return __hip_atomic_load(p, __ATOMIC_RELAXED, __HIP_MEMORY_SCOPE_AGENT); }
; __device__ __forceinline__ unsigned xb_add(unsigned* p, unsigned v) { return __hip_atomic_fetch_add(p, v, __ATOMIC_RELAXED, __HIP_MEMORY_SCOPE_AGENT); }
; #define XB_SPIN(cond, bar) do { unsigned _sp = 0; while (cond) { __builtin_amdgcn_s_sleep(1); \
;     if ((++_sp & 255u) == 0u) { if (xb_ld(&(bar)[XB_TMO])) break; if (_sp > XB_SPIN_CAP) { atomicAdd(&(bar)[XB_TMO], 1u); break; } } } } while (0)
; __device__ __forceinline__ void grid_barrier(unsigned* bar, unsigned x, volatile LAS unsigned* st, unsigned G, int wv) {
;     ...
;         const unsigned old = xb_add(&bar[XB_XSUB(x)], 1u);
;         const unsigned gen = old / nloc;
;         if (old + 1u == (gen + 1u) * nloc) {
;             __builtin_amdgcn_fence(__ATOMIC_RELEASE, "agent");
;             asm volatile("s_waitcnt vmcnt(0)" ::: "memory");
;             const unsigned og = xb_add(&bar[XB_TOP], 1u);
;             const unsigned tg = og / nx;
;             if (og + 1u == (tg + 1u) * nx) xb_add(&bar[XB_TOPGEN], 1u);
;             else XB_SPIN(xb_ld(&bar[XB_TOPGEN]) == tg, bar);
;             __builtin_amdgcn_fence(__ATOMIC_ACQUIRE, "agent");
;             xb_add(&bar[XB_XGEN(x)], 1u);
;             asm volatile("s_waitcnt vmcnt(0)" ::: "memory");
;         } else {
;             XB_SPIN(xb_ld(&bar[XB_XGEN(x)]) == gen, bar);
;             __builtin_amdgcn_fence(__ATOMIC_ACQUIRE, "agent");
.LBB0_424:
	s_or_b64 exec, exec, s[8:9]
	v_cvt_f32_u32_e32 v4, v2
	s_waitcnt vmcnt(0)
	v_readfirstlane_b32 s6, v3
	v_sub_u32_e32 v3, 0, v2
	v_rcp_iflag_f32_e32 v4, v4
	v_add_u32_e32 v5, s6, v1
	v_mul_f32_e32 v4, 0x4f7ffffe, v4
	v_cvt_u32_f32_e32 v4, v4
	v_mul_lo_u32 v1, v3, v4
	v_mul_hi_u32 v1, v4, v1
	v_add_u32_e32 v1, v4, v1
	v_mul_hi_u32 v1, v5, v1
	v_mul_lo_u32 v3, v1, v2
	v_sub_u32_e32 v3, v5, v3
	v_add_u32_e32 v4, 1, v1
	v_cmp_ge_u32_e32 vcc, v3, v2
	s_nop 1
	v_cndmask_b32_e32 v1, v1, v4, vcc
	v_sub_u32_e32 v4, v3, v2
	v_cndmask_b32_e32 v3, v3, v4, vcc
	v_add_u32_e32 v4, 1, v1
	v_cmp_ge_u32_e32 vcc, v3, v2
	v_add_u32_e32 v3, 1, v5
	s_nop 0
	v_cndmask_b32_e32 v1, v1, v4, vcc
	v_mul_lo_u32 v4, v2, v1
	v_add_u32_e32 v2, v4, v2
	v_cmp_ne_u32_e32 vcc, v3, v2
	s_and_saveexec_b64 s[6:7], vcc
	s_xor_b64 s[6:7], exec, s[6:7]
	s_cbranch_execz .LBB0_438
	s_waitcnt lgkmcnt(0)
	buffer_inv sc1
	v_mov_b32_e32 v0, 0x2000
	global_load_dword v0, v0, s[4:5] offset:1024 sc1
	s_add_u32 s10, s4, 0x2400
	s_addc_u32 s11, s5, 0
	s_waitcnt vmcnt(0)
	v_cmp_eq_u32_e32 vcc, v0, v1
	s_and_saveexec_b64 s[8:9], vcc
	s_cbranch_execz .LBB0_437
	s_mov_b32 s22, 1
	s_mov_b64 s[12:13], 0
	v_mov_b32_e32 v0, 0
	s_branch .LBB0_428

; __device__ __forceinline__ unsigned xb_ld(unsigned* p)              { return __hip_atomic_load(p, __ATOMIC_RELAXED, __HIP_MEMORY_SCOPE_AGENT); }
; #define XB_SPIN(cond, bar) do { unsigned _sp = 0; while (cond) { __builtin_amdgcn_s_sleep(1); \
;     if ((++_sp & 255u) == 0u) { if (xb_ld(&(bar)[XB_TMO])) break; if (_sp > XB_SPIN_CAP) { atomicAdd(&(bar)[XB_TMO], 1u); break; } } } } while (0)
; __device__ __forceinline__ void grid_barrier(unsigned* bar, unsigned x, volatile LAS unsigned* st, unsigned G, int wv) {
;     ...
;             XB_SPIN(xb_ld(&bar[XB_XGEN(x)]) == gen, bar);
;             __builtin_amdgcn_fence(__ATOMIC_ACQUIRE, "agent");
;             asm volatile("s_waitcnt vmcnt(0)" ::: "memory");
.LBB0_437:
	s_or_b64 exec, exec, s[8:9]
	s_waitcnt vmcnt(0)
	s_waitcnt vmcnt(0)
